# P1 slack rebalancing: workgroups 0..63 take all second-round weight-conversion items (own stride), the others convert one item per wave; workgroups 0..63 skip straight to the barrier after converting
# speedup vs baseline: 1.0029x; 1.0029x over previous
; #define LAS __attribute__((address_space(3)))
; __global__ void __launch_bounds__(512, 2) mk_fwd(Args a) {
;     ...
;             if (bx >= 64 && rp == 0) {
;                 LAS float* scr = (LAS float*)(lds + wave * 16640);
;                 const int gw = (bx - 64) * 8 + wave, NGW = (G - 64) * 8;
;                 constexpr int I_GLU = (512 / 64) * (1024 / 64), I_OUT = (DM / 64) * (DM / 64), I_1 = (DM / 64) * (FF / 64), I_2 = (FF / 64) * (DM / 64);
;                 for (int it = gw; it < I_GLU + I_OUT + I_1 + I_2; it += NGW) {
;                     int r = it;
;                     if (r < I_GLU) { p0_transpose_item<1>(a.w_glu + (size_t)layer * 512 * 1024, 512, 1024, nullptr, WGLU, scr, r, lane); continue; } r -= I_GLU;
;                     if (r < I_OUT) { p0_transpose_item<0>(a.w_out + (size_t)layer * DM * DM, DM, DM, nullptr, WOUT, scr, r, lane); continue; } r -= I_OUT;
;                     if (r < I_1) { p0_transpose_item<0>(a.w_ff1 + (size_t)layer * DM * FF, DM, FF, a.norm2 + layer * DM, W1, scr, r, lane); continue; } r -= I_1;
;                     p0_transpose_item<0>(a.w_ff2 + (size_t)layer * FF * DM, FF, DM, nullptr, W2, scr, r, lane);
.Ldt_b_norm:
	s_add_i32 s98, s49, 0xc0
	s_cmp_lt_i32 s49, 64
	s_cselect_b32 s98, s98, s84
	v_ashrrev_i32_e32 v0, 6, v184
	s_movk_i32 s5, 0x4100
	s_waitcnt lgkmcnt(0)
	v_mul_lo_u32 v1, v0, s5
	v_lshl_add_u32 v69, s98, 3, v0
	v_lshlrev_b32_e32 v0, 2, v184
	v_and_b32_e32 v2, 60, v0
	v_lshlrev_b32_e32 v0, 3, v184
	v_and_b32_e32 v91, 56, v0
	v_bfe_u32 v90, v184, 3, 3
	v_add_u32_e32 v1, 0, v1
	v_bfe_u32 v68, v184, 4, 2
	v_mul_u32_u24_e32 v0, 0x104, v91
	v_lshlrev_b32_e32 v3, 2, v90
	s_movk_i32 s5, 0x980
	v_lshl_add_u32 v71, v2, 2, v1
	s_movk_i32 s1, 0x104
	v_add3_u32 v87, v1, v0, v3
	v_or_b32_e32 v0, 4, v68
	v_mov_b32_e32 v1, 0x1450
	v_cmp_gt_i32_e32 vcc, s5, v69
	v_mad_u32_u24 v86, v68, s1, v71
	v_mul_u32_u24_e32 v88, 0x104, v0
	v_mad_u32_u24 v89, v0, s1, v1
	v_lshlrev_b32_e32 v72, 2, v2
	v_lshlrev_b32_e32 v70, 6, v69
	s_and_saveexec_b64 s[20:21], vcc
	s_cbranch_execz .LBB0_355
	v_readlane_b32 s8, v254, 53
	v_mov_b32_e32 v1, 0x410
	v_mov_b32_e32 v2, 0xc30
	v_readlane_b32 s9, v254, 54
	v_mad_u32_u24 v1, v0, s1, v1
	v_mad_u32_u24 v0, v0, s1, v2
	s_mov_b32 s16, s8
	s_lshl_b32 s8, s8, 22
	s_mov_b32 s9, s59
	s_mov_b32 s1, s36
	s_mov_b32 s3, s37
	v_readlane_b32 s36, v253, 1
	s_lshl_b64 s[8:9], s[8:9], 2
	v_readlane_b32 s40, v253, 5
	v_readlane_b32 s12, v255, 36
	v_readlane_b32 s41, v253, 6
	s_add_u32 s10, s40, s8
	v_readlane_b32 s13, v255, 37
	v_readlane_b32 s5, v255, 40
	v_readlane_b32 s38, v253, 3
	s_addc_u32 s11, s41, s9
	v_readlane_b32 s14, v255, 38
	v_readlane_b32 s15, v255, 39
	s_and_b32 s13, s5, 0xffff
	v_readlane_b32 s39, v253, 4
	v_mov_b32_e32 v73, v201
	v_writelane_b32 v255, s12, 36
	s_add_u32 s8, s38, s8
	v_lshl_add_u64 v[74:75], s[10:11], 0, v[72:73]
	v_writelane_b32 v255, s13, 37
	s_addc_u32 s9, s39, s9
	s_lshl_b32 s10, s16, 10
	s_mov_b32 s11, s59
	v_writelane_b32 v255, s14, 38
	s_lshl_b64 s[10:11], s[10:11], 2
	v_readlane_b32 s37, v253, 2
	v_writelane_b32 v255, s15, 39
	v_readlane_b32 s12, v254, 55
	s_add_u32 s24, s36, s10
	v_readlane_b32 s13, v254, 56
	s_mov_b32 s36, s1
	s_addc_u32 s25, s37, s11
	v_lshl_add_u64 v[76:77], s[8:9], 0, v[72:73]
	v_readlane_b32 s1, v255, 35
	s_lshl_b32 s8, s16, 20
	s_mov_b32 s9, s59
	s_mov_b64 s[10:11], s[64:65]
	v_readlane_b32 s64, v253, 25
	s_and_b32 s13, s1, 0xffff
	s_lshl_b64 s[8:9], s[8:9], 2
	v_readlane_b32 s78, v253, 39
	v_readlane_b32 s79, v253, 40
	s_add_u32 s8, s78, s8
	v_readlane_b32 s15, v254, 58
	s_addc_u32 s9, s79, s9
	v_readlane_b32 s14, v254, 57
	s_mov_b32 s15, s95
	v_lshl_add_u64 v[78:79], s[8:9], 0, v[72:73]
	v_readlane_b32 s1, v255, 34
	s_lshl_b32 s8, s16, 19
	s_mov_b32 s9, s59
	v_writelane_b32 v254, s12, 55
	v_readlane_b32 s76, v253, 37
	s_and_b32 s1, s1, 0xffff
	s_lshl_b64 s[8:9], s[8:9], 2
	v_writelane_b32 v254, s13, 56
	v_readlane_b32 s77, v253, 38
	s_add_u32 s8, s76, s8
	v_readlane_b32 s42, v253, 7
	s_mov_b32 s37, s3
	v_writelane_b32 v254, s14, 57
	v_readlane_b32 s65, v253, 26
	s_addc_u32 s9, s77, s9
	v_readlane_b32 s5, v255, 32
	v_lshlrev_b32_e32 v2, 10, v90
	s_mov_b32 s42, s18
	v_or_b32_e32 v92, 8, v90
	v_or_b32_e32 v93, 16, v90
	v_or_b32_e32 v94, 24, v90
	v_or_b32_e32 v95, 32, v90
	v_or_b32_e32 v96, 40, v90
	v_or_b32_e32 v97, 48, v90
	v_or_b32_e32 v98, 56, v90
	v_writelane_b32 v254, s15, 58
	s_mov_b64 s[64:65], s[10:11]
	s_mov_b32 s3, s95
	v_lshl_add_u64 v[80:81], s[8:9], 0, v[72:73]
	s_mov_b32 s7, s95
	s_and_b32 s5, s5, 0xffff
	v_lshl_or_b32 v73, v69, 16, v2
	s_lshl_b32 s8, s37, 16
	v_lshlrev_b32_e32 v99, 6, v69
	s_lshl_b32 s9, s37, 6
	v_lshlrev_b32_e32 v100, 2, v69
	s_lshl_b32 s16, s37, 2
	s_cmp_lt_i32 s49, 64
	s_cselect_b32 s99, 0x200, s37
	s_lshl_b32 s8, s99, 16
	s_lshl_b32 s9, s99, 6
	s_lshl_b32 s16, s99, 2
	s_mov_b64 s[28:29], 0
	v_add_u32_e32 v101, v71, v1
	v_add_u32_e32 v102, v71, v0
	v_mov_b32_e32 v103, v69
	v_readlane_b32 s43, v253, 8
	v_readlane_b32 s66, v253, 27
	v_readlane_b32 s67, v253, 28
	v_readlane_b32 s68, v253, 29
	v_readlane_b32 s69, v253, 30
	v_readlane_b32 s70, v253, 31
	v_readlane_b32 s71, v253, 32
	v_readlane_b32 s72, v253, 33
	v_readlane_b32 s73, v253, 34
	v_readlane_b32 s74, v253, 35
	v_readlane_b32 s75, v253, 36
	s_branch .LBB0_311
.LBB0_310:
	s_or_b64 exec, exec, s[10:11]
	v_add_u32_e32 v103, s99, v103
	s_movk_i32 s10, 0x5ff
	s_cmp_lt_i32 s49, 64
	s_cselect_b32 s10, 0x97f, s10
	v_cmp_lt_i32_e32 vcc, s10, v103
	v_add_u32_e32 v73, s8, v73
	v_add_u32_e32 v99, s9, v99
	s_or_b64 s[28:29], vcc, s[28:29]
	v_add_u32_e32 v100, s16, v100
	s_andn2_b64 exec, exec, s[28:29]
	s_cbranch_execz .LBB0_355

; #define GSYNC() do { for (int rs_ = 0; rs_ < REP_SYNC; ++rs_) xcd_barrier(xbar); } while (0)
; __global__ void __launch_bounds__(512, 2) mk_fwd(Args a) {
;     ...
;                 if (layer + 1 < DEPTH) for (int it = gw; it < (DM / 64) * (INW / 64); it += NGW) p0_transpose_item<0>(a.w_in + (size_t)(layer + 1) * DM * INW, DM, INW, a.norm1 + (layer + 1) * DM, WINN, scr, it, lane);
;                 __syncthreads(); ssm_gen(lds, a, layer, (bx - 64) >> 3, (bx - 64) & 7);
;             }
;         }
;         GSYNC();
.Ldt_skipconv:
	s_cmp_lt_i32 s49, 64
	s_cbranch_scc1 .LBB0_388
	v_mov_b32_e32 v12, v236
	s_waitcnt vmcnt(0) lgkmcnt(0)
	s_barrier
	v_readlane_b32 vcc_lo, v255, 56
	s_cmp_lg_u32 vcc_lo, 1
	s_cbranch_scc1 .Ldt_c_norm
	v_writelane_b32 v255, 2, 56
	v_readlane_b32 s13, v255, 55
	v_readlane_b32 s14, v255, 57
	v_readlane_b32 s15, v255, 58
	v_readlane_b32 s20, v255, 59
	v_readlane_b32 s21, v255, 60
	v_readlane_b32 s24, v255, 61
	v_readlane_b32 s25, v255, 62
	v_readlane_b32 s42, v255, 63
	s_nop 3
	s_branch .LBB0_152
